# attention interval loop: wave-uniform branch tests read the SGPR mask directly (s_and with exec) instead of v_cndmask + v_cmp_ne
# baseline (speedup 1.0000x reference)
; #define LAS __attribute__((address_space(3)))
; #define MFMA32(a, b, c) __builtin_amdgcn_mfma_f32_32x32x16_bf16((a), (b), (c), 0, 0, 0)
; __device__ __forceinline__ void flash_mask(f32x16& s0, f32x16& s1, int lo, int hi, int h) {
; #pragma unroll
;     for (int i = 0; i < 16; ++i) { const int key = (i & 3) + 8 * (i >> 2) + 4 * h;
;         s0[i] = (key >= lo && key <= hi) ? s0[i] : -INFINITY; s1[i] = (key + 32 >= lo && key + 32 <= hi) ? s1[i] : -INFINITY; }
; __device__ __forceinline__ void flash_pair(FlashState& S, const LAS unsigned char* ka, const LAS unsigned char* va, const LAS unsigned char* kb2, const LAS unsigned char* vb2, ...
;     bf16x8 kf[8]; f32x16 a0, a1, b0, b1;
;     flash_kload(ka, r, h, kf);
;     { const float init = A.en ? -S.m : -INFINITY;
; #pragma unroll
;         for (int i = 0; i < 16; ++i) { a0[i] = init; a1[i] = init; }
; #pragma unroll
;         for (int ks = 0; ks < 4; ++ks) { a0 = MFMA32(kf[2 * ks], qf[ks], a0); a1 = MFMA32(kf[2 * ks + 1], qf[ks], a1); } }
;     if (A.masked) flash_mask(a0, a1, A.lo, A.hi, h);
.LBB0_861:
	s_or_b64 s[24:25], s[66:67], s[44:45]
	s_cmp_lt_i32 s22, 32
	s_cselect_b64 vcc, -1, 0
	s_sub_i32 s23, s22, 32
	v_lshrrev_b32_e32 v34, s22, v132
	v_lshrrev_b32_e32 v35, s23, v133
	v_cndmask_b32_e32 v34, v35, v34, vcc
	v_and_b32_e32 v34, 1, v34
	v_cmp_eq_u32_e32 vcc, 1, v34
	s_or_b64 s[24:25], s[24:25], vcc
	s_cmp_lt_i32 s74, 0
	s_cselect_b64 s[76:77], -1, 0
	s_cmp_gt_i32 s74, -1
	s_cselect_b64 s[26:27], -1, 0
	s_or_b64 vcc, s[66:67], s[76:77]
	s_cmp_lt_i32 s74, 32
	s_cselect_b64 s[42:43], -1, 0
	s_sub_i32 s23, s74, 32
	v_lshrrev_b32_e32 v35, s74, v132
	v_lshrrev_b32_e32 v36, s23, v133
	v_cndmask_b32_e64 v34, 0, 1, s[26:27]
	v_cndmask_b32_e64 v35, v36, v35, s[42:43]
	v_cndmask_b32_e32 v34, v35, v34, vcc
	v_and_b32_e32 v34, 1, v34
	v_cmp_eq_u32_e64 s[42:43], 1, v34
	s_or_b64 s[26:27], s[24:25], s[42:43]
	s_and_b64 vcc, exec, s[26:27]
	s_cbranch_vccz .LBB0_874
	v_add_u32_e32 v174, s28, v127
	ds_read_b128 v[34:37], v174
	ds_read_b128 v[38:41], v174 offset:512
	ds_read_b128 v[42:45], v174 offset:2048
	ds_read_b128 v[46:49], v174 offset:2560
	ds_read_b128 v[50:53], v174 offset:4096
	ds_read_b128 v[54:57], v174 offset:4608
	ds_read_b128 v[58:61], v174 offset:6144
	ds_read_b128 v[62:65], v174 offset:6656
	s_cmp_eq_u32 s22, s8
	s_cselect_b64 s[46:47], -1, 0
	s_cmp_eq_u32 s22, s34
	s_cselect_b64 s[22:23], -1, 0
	s_and_b64 s[48:49], s[66:67], s[22:23]
	s_or_b64 s[22:23], s[46:47], s[48:49]
	v_cndmask_b32_e64 v66, v233, -v173, s[24:25]
	v_mov_b32_e32 v67, v66
	v_mov_b32_e32 v68, v66
	v_mov_b32_e32 v69, v66
	v_mov_b32_e32 v70, v66
	v_mov_b32_e32 v71, v66
	v_mov_b32_e32 v72, v66
	v_mov_b32_e32 v73, v66
	v_mov_b32_e32 v74, v66
	v_mov_b32_e32 v75, v66
	v_mov_b32_e32 v76, v66
	v_mov_b32_e32 v77, v66
	v_mov_b32_e32 v78, v66
	v_mov_b32_e32 v79, v66
	v_mov_b32_e32 v80, v66
	v_mov_b32_e32 v81, v66
	s_andn2_b64 vcc, exec, s[22:23]
	s_waitcnt lgkmcnt(7)
	v_mfma_f32_32x32x16_bf16 v[82:97], v[34:37], v[108:111], v[66:81]
	s_waitcnt lgkmcnt(6)
	v_mfma_f32_32x32x16_bf16 v[66:81], v[38:41], v[108:111], v[66:81]
	s_waitcnt lgkmcnt(5)
	v_mfma_f32_32x32x16_bf16 v[82:97], v[42:45], v[100:103], v[82:97]
	s_waitcnt lgkmcnt(4)
	v_mfma_f32_32x32x16_bf16 v[66:81], v[46:49], v[100:103], v[66:81]
	s_waitcnt lgkmcnt(3)
	v_mfma_f32_32x32x16_bf16 v[82:97], v[50:53], v[104:107], v[82:97]
	s_waitcnt lgkmcnt(2)
	v_mfma_f32_32x32x16_bf16 v[66:81], v[54:57], v[104:107], v[66:81]
	s_waitcnt lgkmcnt(1)
	v_mfma_f32_32x32x16_bf16 v[82:97], v[58:61], v[112:115], v[82:97]
	s_waitcnt lgkmcnt(0)
	v_mfma_f32_32x32x16_bf16 v[66:81], v[62:65], v[112:115], v[66:81]
	s_cbranch_vccnz .LBB0_864
	v_cndmask_b32_e64 v34, 63, v1, s[46:47]
	v_cndmask_b32_e64 v35, 0, v124, s[48:49]
	v_cmp_lt_i32_e32 vcc, v138, v35
	v_cmp_gt_i32_e64 s[46:47], v138, v34
	s_or_b64 vcc, s[46:47], vcc
	s_nop 4
	v_cndmask_b32_e32 v82, v82, v233, vcc
	v_cmp_lt_i32_e32 vcc, v139, v35
	v_cmp_gt_i32_e64 s[46:47], v139, v34
	s_or_b64 vcc, s[46:47], vcc
	v_cndmask_b32_e32 v66, v66, v233, vcc
	v_cmp_lt_i32_e32 vcc, v172, v35
	v_cmp_ge_i32_e64 s[46:47], v138, v34
	s_or_b64 vcc, s[46:47], vcc
	v_cndmask_b32_e32 v83, v83, v233, vcc
	v_cmp_lt_i32_e32 vcc, v140, v35
	v_cmp_gt_i32_e64 s[46:47], v140, v34
	s_or_b64 vcc, s[46:47], vcc
	v_cndmask_b32_e32 v67, v67, v233, vcc
	v_cmp_lt_i32_e32 vcc, v141, v35
	v_cmp_gt_i32_e64 s[46:47], v141, v34
	s_or_b64 vcc, s[46:47], vcc
	v_cndmask_b32_e32 v84, v84, v233, vcc
	v_cmp_lt_i32_e32 vcc, v142, v35
	v_cmp_gt_i32_e64 s[46:47], v142, v34
	s_or_b64 vcc, s[46:47], vcc
	v_cndmask_b32_e32 v68, v68, v233, vcc
	v_cmp_lt_i32_e32 vcc, v143, v35
	v_cmp_gt_i32_e64 s[46:47], v143, v34
	s_or_b64 vcc, s[46:47], vcc
	v_cndmask_b32_e32 v85, v85, v233, vcc
	v_cmp_lt_i32_e32 vcc, v144, v35
	v_cmp_gt_i32_e64 s[46:47], v144, v34
	s_or_b64 vcc, s[46:47], vcc
	v_cndmask_b32_e32 v69, v69, v233, vcc
	v_cmp_lt_i32_e32 vcc, v145, v35
	v_cmp_gt_i32_e64 s[46:47], v145, v34
	s_or_b64 vcc, s[46:47], vcc
	v_cndmask_b32_e32 v86, v86, v233, vcc
	v_cmp_lt_i32_e32 vcc, v146, v35
	v_cmp_gt_i32_e64 s[46:47], v146, v34
	s_or_b64 vcc, s[46:47], vcc
	v_cndmask_b32_e32 v70, v70, v233, vcc
	v_cmp_lt_i32_e32 vcc, v147, v35
	v_cmp_gt_i32_e64 s[46:47], v147, v34
	s_or_b64 vcc, s[46:47], vcc
	v_cndmask_b32_e32 v87, v87, v233, vcc
	v_cmp_lt_i32_e32 vcc, v148, v35
	v_cmp_gt_i32_e64 s[46:47], v148, v34
	s_or_b64 vcc, s[46:47], vcc
	v_cndmask_b32_e32 v71, v71, v233, vcc
	v_cmp_lt_i32_e32 vcc, v149, v35
	v_cmp_gt_i32_e64 s[46:47], v149, v34
	s_or_b64 vcc, s[46:47], vcc
	v_cndmask_b32_e32 v88, v88, v233, vcc
	v_cmp_lt_i32_e32 vcc, v150, v35
	v_cmp_gt_i32_e64 s[46:47], v150, v34
	s_or_b64 vcc, s[46:47], vcc
	v_cndmask_b32_e32 v72, v72, v233, vcc
	v_cmp_lt_i32_e32 vcc, v151, v35
	v_cmp_gt_i32_e64 s[46:47], v151, v34
	s_or_b64 vcc, s[46:47], vcc
	v_cndmask_b32_e32 v89, v89, v233, vcc
	v_cmp_lt_i32_e32 vcc, v152, v35
	v_cmp_gt_i32_e64 s[46:47], v152, v34
	s_or_b64 vcc, s[46:47], vcc
	v_cndmask_b32_e32 v73, v73, v233, vcc
	v_cmp_lt_i32_e32 vcc, v153, v35
	v_cmp_gt_i32_e64 s[46:47], v153, v34
	s_or_b64 vcc, s[46:47], vcc
	v_cndmask_b32_e32 v90, v90, v233, vcc
	v_cmp_lt_i32_e32 vcc, v154, v35
	v_cmp_gt_i32_e64 s[46:47], v154, v34
	s_or_b64 vcc, s[46:47], vcc
	v_cndmask_b32_e32 v74, v74, v233, vcc
	v_cmp_lt_i32_e32 vcc, v155, v35
	v_cmp_gt_i32_e64 s[46:47], v155, v34
	s_or_b64 vcc, s[46:47], vcc
; __device__ __forceinline__ void flash_mask(f32x16& s0, f32x16& s1, int lo, int hi, int h) {
; #pragma unroll
;     for (int i = 0; i < 16; ++i) { const int key = (i & 3) + 8 * (i >> 2) + 4 * h;
;         s0[i] = (key >= lo && key <= hi) ? s0[i] : -INFINITY; s1[i] = (key + 32 >= lo && key + 32 <= hi) ? s1[i] : -INFINITY; }
; }
; __device__ __forceinline__ float flash_rowmax(const f32x16& s0, const f32x16& s1) {
;     float mx = -INFINITY;
; #pragma unroll
;     for (int i = 0; i < 16; ++i) asm("v_max3_f32 %0, %1, %2, %3" : "=v"(mx) : "v"(mx), "v"(s0[i]), "v"(s1[i]));
;     return xhalf_max(mx);
; }
; __device__ __forceinline__ void flash_pair(FlashState& S, const LAS unsigned char* ka, const LAS unsigned char* va, const LAS unsigned char* kb2, const LAS unsigned char* vb2, ...
;     ...
;     { const float mx = flash_rowmax(a0, a1);
;         if (__ballot(mx > SM_THR || (first && mx < -SM_THR)) != 0ull) { const float d = (mx > NEG_BIG) ? (first ? mx : fmaxf(mx, 0.f)) : 0.f, alpha = __builtin_amdgcn_exp2f(-d); S.m += d; S.l *= alpha;
; #pragma unroll
;             for (int i = 0; i < 16; ++i) { S.o[0][i] *= alpha; S.o[1][i] *= alpha; a0[i] -= d; a1[i] -= d; } } }
	v_cndmask_b32_e32 v91, v91, v233, vcc
	v_cmp_lt_i32_e32 vcc, v156, v35
	v_cmp_gt_i32_e64 s[46:47], v156, v34
	s_or_b64 vcc, s[46:47], vcc
	v_cndmask_b32_e32 v75, v75, v233, vcc
	v_cmp_lt_i32_e32 vcc, v157, v35
	v_cmp_gt_i32_e64 s[46:47], v157, v34
	s_or_b64 vcc, s[46:47], vcc
	v_cndmask_b32_e32 v92, v92, v233, vcc
	v_cmp_lt_i32_e32 vcc, v158, v35
	v_cmp_gt_i32_e64 s[46:47], v158, v34
	s_or_b64 vcc, s[46:47], vcc
	v_cndmask_b32_e32 v76, v76, v233, vcc
	v_cmp_lt_i32_e32 vcc, v159, v35
	v_cmp_gt_i32_e64 s[46:47], v159, v34
	s_or_b64 vcc, s[46:47], vcc
	v_cndmask_b32_e32 v93, v93, v233, vcc
	v_cmp_lt_i32_e32 vcc, v160, v35
	v_cmp_gt_i32_e64 s[46:47], v160, v34
	s_or_b64 vcc, s[46:47], vcc
	v_cndmask_b32_e32 v77, v77, v233, vcc
	v_cmp_lt_i32_e32 vcc, v161, v35
	v_cmp_gt_i32_e64 s[46:47], v161, v34
	s_or_b64 vcc, s[46:47], vcc
	v_cndmask_b32_e32 v94, v94, v233, vcc
	v_cmp_lt_i32_e32 vcc, v162, v35
	v_cmp_gt_i32_e64 s[46:47], v162, v34
	s_or_b64 vcc, s[46:47], vcc
	v_cndmask_b32_e32 v78, v78, v233, vcc
	v_cmp_lt_i32_e32 vcc, v163, v35
	v_cmp_gt_i32_e64 s[46:47], v163, v34
	s_or_b64 vcc, s[46:47], vcc
	v_cndmask_b32_e32 v95, v95, v233, vcc
	v_cmp_lt_i32_e32 vcc, v164, v35
	v_cmp_gt_i32_e64 s[46:47], v164, v34
	s_or_b64 vcc, s[46:47], vcc
	v_cndmask_b32_e32 v79, v79, v233, vcc
	v_cmp_lt_i32_e32 vcc, v165, v35
	v_cmp_gt_i32_e64 s[46:47], v165, v34
	s_or_b64 vcc, s[46:47], vcc
	v_cndmask_b32_e32 v96, v96, v233, vcc
	v_cmp_lt_i32_e32 vcc, v166, v35
	v_cmp_gt_i32_e64 s[46:47], v166, v34
	s_or_b64 vcc, s[46:47], vcc
	v_cndmask_b32_e32 v80, v80, v233, vcc
	v_cmp_lt_i32_e32 vcc, v167, v35
	v_cmp_gt_i32_e64 s[46:47], v167, v34
	s_or_b64 vcc, s[46:47], vcc
	v_cndmask_b32_e32 v97, v97, v233, vcc
	v_cmp_lt_i32_e32 vcc, v168, v35
	v_cmp_gt_i32_e64 s[46:47], v168, v34
	s_or_b64 vcc, s[46:47], vcc
	v_cndmask_b32_e32 v81, v81, v233, vcc
.LBB0_864:
	v_max3_f32 v34, v233, v82, v66
	s_mov_b32 s22, 0xc1000000
	v_max3_f32 v34, v34, v83, v67
	s_nop 0
	v_max3_f32 v34, v34, v84, v68
	s_nop 0
	v_max3_f32 v34, v34, v85, v69
	s_nop 0
	v_max3_f32 v34, v34, v86, v70
	s_nop 0
	v_max3_f32 v34, v34, v87, v71
	v_max3_f32 v34, v34, v88, v72
	v_max3_f32 v34, v34, v89, v73
	v_max3_f32 v34, v34, v90, v74
	v_max3_f32 v34, v34, v91, v75
	v_max3_f32 v34, v34, v92, v76
	v_max3_f32 v34, v34, v93, v77
	v_max3_f32 v34, v34, v94, v78
	v_max3_f32 v34, v34, v95, v79
	v_max3_f32 v34, v34, v96, v80
	v_max3_f32 v34, v34, v97, v81
	v_mov_b32_e32 v35, v34
	s_nop 1
	v_permlane32_swap_b32_e32 v34, v35
	v_max_f32_e32 v35, v35, v35
	v_max_f32_e32 v34, v34, v34
	v_max_f32_e32 v34, v34, v35
	v_cmp_gt_f32_e64 s[46:47], s22, v34
	v_cmp_lt_f32_e32 vcc, s33, v34
	s_and_b64 s[22:23], s[44:45], s[46:47]
	s_or_b64 s[22:23], vcc, s[22:23]
	s_and_b64 vcc, exec, s[22:23]
	s_cbranch_vccz .LBB0_866
	v_max_f32_e32 v35, v34, v34
	v_max_f32_e32 v35, 0, v35
	v_cndmask_b32_e64 v35, v35, v34, s[44:45]
	v_cmp_lt_f32_e32 vcc, s12, v34
	s_nop 1
	v_cndmask_b32_e32 v34, 0, v35, vcc
	v_exp_f32_e64 v36, -v34
	v_add_f32_e32 v173, v173, v34
	v_pk_add_f32 v[82:83], v[82:83], v[34:35] op_sel_hi:[1,0] neg_lo:[0,1] neg_hi:[0,1]
	v_pk_add_f32 v[66:67], v[66:67], v[34:35] op_sel_hi:[1,0] neg_lo:[0,1] neg_hi:[0,1]
	v_mul_f32_e32 v176, v176, v36
	v_pk_add_f32 v[84:85], v[84:85], v[34:35] op_sel_hi:[1,0] neg_lo:[0,1] neg_hi:[0,1]
	v_pk_add_f32 v[68:69], v[68:69], v[34:35] op_sel_hi:[1,0] neg_lo:[0,1] neg_hi:[0,1]
	v_pk_add_f32 v[86:87], v[86:87], v[34:35] op_sel_hi:[1,0] neg_lo:[0,1] neg_hi:[0,1]
	v_pk_add_f32 v[70:71], v[70:71], v[34:35] op_sel_hi:[1,0] neg_lo:[0,1] neg_hi:[0,1]
	v_pk_add_f32 v[88:89], v[88:89], v[34:35] op_sel_hi:[1,0] neg_lo:[0,1] neg_hi:[0,1]
	v_pk_add_f32 v[72:73], v[72:73], v[34:35] op_sel_hi:[1,0] neg_lo:[0,1] neg_hi:[0,1]
	v_pk_add_f32 v[90:91], v[90:91], v[34:35] op_sel_hi:[1,0] neg_lo:[0,1] neg_hi:[0,1]
	v_pk_add_f32 v[74:75], v[74:75], v[34:35] op_sel_hi:[1,0] neg_lo:[0,1] neg_hi:[0,1]
	v_pk_add_f32 v[92:93], v[92:93], v[34:35] op_sel_hi:[1,0] neg_lo:[0,1] neg_hi:[0,1]
	v_pk_add_f32 v[76:77], v[76:77], v[34:35] op_sel_hi:[1,0] neg_lo:[0,1] neg_hi:[0,1]
	v_pk_add_f32 v[94:95], v[94:95], v[34:35] op_sel_hi:[1,0] neg_lo:[0,1] neg_hi:[0,1]
	v_pk_add_f32 v[78:79], v[78:79], v[34:35] op_sel_hi:[1,0] neg_lo:[0,1] neg_hi:[0,1]
	v_pk_mul_f32 v[32:33], v[32:33], v[36:37] op_sel_hi:[1,0]
	v_pk_mul_f32 v[30:31], v[30:31], v[36:37] op_sel_hi:[1,0]
	v_pk_mul_f32 v[28:29], v[28:29], v[36:37] op_sel_hi:[1,0]
	v_pk_mul_f32 v[26:27], v[26:27], v[36:37] op_sel_hi:[1,0]
	v_pk_mul_f32 v[24:25], v[24:25], v[36:37] op_sel_hi:[1,0]
	v_pk_mul_f32 v[22:23], v[22:23], v[36:37] op_sel_hi:[1,0]
	v_pk_mul_f32 v[20:21], v[20:21], v[36:37] op_sel_hi:[1,0]
	v_pk_mul_f32 v[18:19], v[18:19], v[36:37] op_sel_hi:[1,0]
	v_pk_mul_f32 v[16:17], v[16:17], v[36:37] op_sel_hi:[1,0]
	v_pk_mul_f32 v[14:15], v[14:15], v[36:37] op_sel_hi:[1,0]
	v_pk_mul_f32 v[12:13], v[12:13], v[36:37] op_sel_hi:[1,0]
	v_pk_mul_f32 v[10:11], v[10:11], v[36:37] op_sel_hi:[1,0]
	v_pk_mul_f32 v[8:9], v[8:9], v[36:37] op_sel_hi:[1,0]
	v_pk_mul_f32 v[6:7], v[6:7], v[36:37] op_sel_hi:[1,0]
	v_pk_mul_f32 v[4:5], v[4:5], v[36:37] op_sel_hi:[1,0]
	v_pk_mul_f32 v[2:3], v[2:3], v[36:37] op_sel_hi:[1,0]
	v_pk_add_f32 v[96:97], v[96:97], v[34:35] op_sel_hi:[1,0] neg_lo:[0,1] neg_hi:[0,1]
	v_pk_add_f32 v[80:81], v[80:81], v[34:35] op_sel_hi:[1,0] neg_lo:[0,1] neg_hi:[0,1]
